# weight conversion loop software-pipelined (next item's loads in flight during the LDS transpose/store of the current one), all matrices handled by the new converter
# speedup vs baseline: 1.1328x; 1.0039x over previous
.LBB0_853:
	s_load_dwordx2 s[6:7], s[0:1], 0x130
	s_waitcnt lgkmcnt(0)
	v_mov_b32_e32 v2, v133
	v_lshrrev_b32_e32 v3, 4, v2
	v_and_b32_e32 v4, 15, v2
	v_lshlrev_b32_e32 v4, 2, v4
	v_mul_u32_u24_e32 v5, 65, v3
	v_add_lshl_u32 v5, v5, v4, 2
	v_and_b32_e32 v7, 63, v2
	v_lshrrev_b32_e32 v27, 6, v2
	v_and_b32_e32 v24, 15, v7
	v_lshrrev_b32_e32 v25, 4, v7
	v_readfirstlane_b32 s22, v27
	v_mul_u32_u24_e32 v6, 520, v25
	v_lshl_add_u32 v6, v27, 4, v6
	v_add_lshl_u32 v6, v6, v24, 2
	v_lshlrev_b32_e32 v26, 4, v7
	s_sub_u32 s14, s24, 2048
	s_mov_b32 s25, s14
	s_cmp_ge_u32 s25, 4240
	s_cbranch_scc1 .Lcp_dec_zero_f
	s_cmp_lt_u32 s25, 656
	s_cbranch_scc1 .Lcp_dec_win_f
	s_cmp_lt_u32 s25, 1680
	s_cbranch_scc1 .Lcp_dec_wm_f
	s_cmp_lt_u32 s25, 1936
	s_cbranch_scc1 .Lcp_dec_wb_f
	s_cmp_lt_u32 s25, 2192
	s_cbranch_scc1 .Lcp_dec_wout_f
	s_cmp_lt_u32 s25, 3216
	s_cbranch_scc1 .Lcp_dec_w1_f
	s_cmp_lt_u32 s25, 4240
	s_cbranch_scc1 .Lcp_dec_w2_f
	s_branch .Lcp_dec_zero_f
.Lcp_dec_win_f:
	s_load_dwordx2 s[20:21], s[0:1], 0x70
	s_mul_i32 s27, s62, 0xa10000
	s_mov_b32 s28, 0x9e7800
	s_mul_i32 s29, s25, 1599
	s_lshr_b32 s29, s29, 16
	s_mul_i32 s26, s29, 41
	s_sub_u32 s26, s25, s26
	s_mov_b32 s25, s29
	s_mov_b32 s18, 2576
	s_mov_b32 s19, 32
	s_mov_b32 s9, 0
	s_mov_b32 s23, 1
	s_waitcnt lgkmcnt(0)
	s_add_u32 s20, s20, s27
	s_addc_u32 s21, s21, 0
	s_branch .Lcp_dec_tile_f
.Lcp_dec_wm_f:
	s_load_dwordx2 s[20:21], s[0:1], 0x100
	s_sub_u32 s25, s25, 656
	s_mul_i32 s27, s62, 0x1000000
	s_mov_b32 s28, 0xf27800
	s_and_b32 s26, s25, 63
	s_lshr_b32 s25, s25, 6
	s_mov_b32 s18, 4096
	s_mov_b32 s19, 32
	s_mov_b32 s9, 1
	s_mov_b32 s23, 0
	s_waitcnt lgkmcnt(0)
	s_add_u32 s20, s20, s27
	s_addc_u32 s21, s21, 0
	s_branch .Lcp_dec_tile_f
.Lcp_dec_wb_f:
	s_load_dwordx2 s[20:21], s[0:1], 0xf8
	s_sub_u32 s25, s25, 1680
	s_mul_i32 s27, s62, 0x400000
	s_mov_b32 s28, 0x1727800
	s_lshr_b32 s26, s25, 6
	s_and_b32 s25, s25, 63
	s_mul_i32 s29, s26, 0x100000
	s_add_u32 s27, s27, s29
	s_lshl_b32 s29, s26, 19
	s_add_u32 s28, s28, s29
	s_and_b32 s26, s25, 15
	s_lshr_b32 s25, s25, 4
	s_mov_b32 s18, 1024
	s_mov_b32 s19, 8
	s_mov_b32 s9, 1
	s_mov_b32 s23, 0
	s_waitcnt lgkmcnt(0)
	s_add_u32 s20, s20, s27
	s_addc_u32 s21, s21, 0
	s_branch .Lcp_dec_tile_f
.Lcp_dec_wout_f:
	s_load_dwordx2 s[20:21], s[0:1], 0x110
	s_sub_u32 s25, s25, 1936
	s_mul_i32 s27, s62, 0x400000
	s_mov_b32 s28, 0x1927800
	s_and_b32 s26, s25, 15
	s_lshr_b32 s25, s25, 4
	s_mov_b32 s18, 1024
	s_mov_b32 s19, 32
	s_mov_b32 s9, 0
	s_mov_b32 s23, 0
	s_waitcnt lgkmcnt(0)
	s_add_u32 s20, s20, s27
	s_addc_u32 s21, s21, 0
	s_branch .Lcp_dec_tile_f
.Lcp_dec_w1_f:
	s_load_dwordx2 s[20:21], s[0:1], 0x118
	s_sub_u32 s25, s25, 2192
	s_mul_i32 s27, s62, 0x1000000
	s_mov_b32 s28, 0x1b27800
	s_and_b32 s26, s25, 63
	s_lshr_b32 s25, s25, 6
	s_mov_b32 s18, 4096
	s_mov_b32 s19, 32
	s_mov_b32 s9, 0
	s_mov_b32 s23, 0
	s_waitcnt lgkmcnt(0)
	s_add_u32 s20, s20, s27
	s_addc_u32 s21, s21, 0
	s_branch .Lcp_dec_tile_f
.Lcp_dec_w2_f:
	s_load_dwordx2 s[20:21], s[0:1], 0x120
	s_sub_u32 s25, s25, 3216
	s_mul_i32 s27, s62, 0x1000000
	s_mov_b32 s28, 0x2327800
	s_and_b32 s26, s25, 15
	s_lshr_b32 s25, s25, 4
	s_mov_b32 s18, 1024
	s_mov_b32 s19, 128
	s_mov_b32 s9, 0
	s_mov_b32 s23, 0
	s_waitcnt lgkmcnt(0)
	s_add_u32 s20, s20, s27
	s_addc_u32 s21, s21, 0
	s_branch .Lcp_dec_tile_f
.Lcp_dec_zero_f:
	s_mov_b32 s9, 3
	s_branch .Lcp_dec_done_f
.Lcp_dec_tile_f:
	s_lshl_b32 s25, s25, 6
	s_lshl_b32 s26, s26, 6
	s_mul_i32 s27, s25, s18
	s_lshl_b32 s27, s27, 2
	s_add_u32 s20, s20, s27
	s_addc_u32 s21, s21, 0
	v_add_u32_e32 v27, s26, v4
	s_sub_u32 s27, s18, 4
	v_min_u32_e32 v27, s27, v27
	v_mul_lo_u32 v28, v3, s18
	v_add_lshl_u32 v28, v28, v27, 2
	s_lshl_b32 s27, s18, 6
	global_load_dwordx4 v[8:11], v28, s[20:21]
	v_add_u32_e32 v28, s27, v28
	global_load_dwordx4 v[12:15], v28, s[20:21]
	v_add_u32_e32 v28, s27, v28
	global_load_dwordx4 v[16:19], v28, s[20:21]
	v_add_u32_e32 v28, s27, v28
	global_load_dwordx4 v[20:23], v28, s[20:21]
	s_mov_b32 s16, 1
	s_lshr_b32 s27, s26, 4
	s_add_u32 s27, s27, s22
	s_lshr_b32 s29, s18, 4
	s_cmp_ge_u32 s27, s29
	s_cbranch_scc0 .Lcp_dec_ok_f
	s_mov_b32 s9, 4
	s_branch .Lcp_dec_done_f
.Lcp_dec_ok_f:
	s_cmp_eq_u32 s9, 1
	s_cbranch_scc1 .Lcp_dec_rm_f
	s_cmp_eq_u32 s23, 0
	s_cbranch_scc1 .Lcp_dec_np_f
	s_cmp_lt_u32 s27, 128
	s_cbranch_scc1 .Lcp_dec_np_f
	s_cmp_eq_u32 s27, 128
	s_cselect_b32 s29, 161, s27
	s_sub_u32 s27, s29, 1
.Lcp_dec_np_f:
	s_mul_i32 s27, s27, s19
	s_lshr_b32 s29, s25, 5
	s_add_u32 s27, s27, s29
	s_lshl_b32 s27, s27, 10
	s_add_u32 s8, s27, s28
	s_branch .Lcp_dec_done_f
.Lcp_dec_rm_f:
	s_lshl_b32 s10, s19, 6
	s_lshl_b32 s27, s27, 4
	s_mul_i32 s27, s27, s10
	s_lshl_b32 s29, s25, 1
	s_add_u32 s27, s27, s29
	s_add_u32 s8, s27, s28
.Lcp_dec_done_f:
.Lcp_loop:
	s_add_u32 s15, s24, s42
	s_mov_b32 s12, 5
	s_mov_b32 s16, 0
	s_cmp_gt_u32 s15, 0x1890
	s_cbranch_scc1 .Lcp_noA
	s_sub_u32 s14, s15, 2048
	s_mov_b32 s25, s14
	s_cmp_ge_u32 s25, 4240
	s_cbranch_scc1 .Lcp_dec_zero_a
	s_cmp_lt_u32 s25, 656
	s_cbranch_scc1 .Lcp_dec_win_a
	s_cmp_lt_u32 s25, 1680
	s_cbranch_scc1 .Lcp_dec_wm_a
	s_cmp_lt_u32 s25, 1936
	s_cbranch_scc1 .Lcp_dec_wb_a
	s_cmp_lt_u32 s25, 2192
	s_cbranch_scc1 .Lcp_dec_wout_a
	s_cmp_lt_u32 s25, 3216
	s_cbranch_scc1 .Lcp_dec_w1_a
	s_cmp_lt_u32 s25, 4240
	s_cbranch_scc1 .Lcp_dec_w2_a
	s_branch .Lcp_dec_zero_a
.Lcp_dec_win_a:
	s_load_dwordx2 s[20:21], s[0:1], 0x70
	s_mul_i32 s27, s62, 0xa10000
	s_mov_b32 s28, 0x9e7800
	s_mul_i32 s29, s25, 1599
	s_lshr_b32 s29, s29, 16
	s_mul_i32 s26, s29, 41
	s_sub_u32 s26, s25, s26
	s_mov_b32 s25, s29
	s_mov_b32 s18, 2576
	s_mov_b32 s19, 32
	s_mov_b32 s12, 0
	s_mov_b32 s23, 1
	s_waitcnt lgkmcnt(0)
	s_add_u32 s20, s20, s27
	s_addc_u32 s21, s21, 0
	s_branch .Lcp_dec_tile_a
.Lcp_dec_wm_a:
	s_load_dwordx2 s[20:21], s[0:1], 0x100
	s_sub_u32 s25, s25, 656
	s_mul_i32 s27, s62, 0x1000000
	s_mov_b32 s28, 0xf27800
	s_and_b32 s26, s25, 63
	s_lshr_b32 s25, s25, 6
	s_mov_b32 s18, 4096
	s_mov_b32 s19, 32
	s_mov_b32 s12, 1
	s_mov_b32 s23, 0
	s_waitcnt lgkmcnt(0)
	s_add_u32 s20, s20, s27
	s_addc_u32 s21, s21, 0
	s_branch .Lcp_dec_tile_a
.Lcp_dec_wb_a:
	s_load_dwordx2 s[20:21], s[0:1], 0xf8
	s_sub_u32 s25, s25, 1680
	s_mul_i32 s27, s62, 0x400000
	s_mov_b32 s28, 0x1727800
	s_lshr_b32 s26, s25, 6
	s_and_b32 s25, s25, 63
	s_mul_i32 s29, s26, 0x100000
	s_add_u32 s27, s27, s29
	s_lshl_b32 s29, s26, 19
	s_add_u32 s28, s28, s29
	s_and_b32 s26, s25, 15
	s_lshr_b32 s25, s25, 4
	s_mov_b32 s18, 1024
	s_mov_b32 s19, 8
	s_mov_b32 s12, 1
	s_mov_b32 s23, 0
	s_waitcnt lgkmcnt(0)
	s_add_u32 s20, s20, s27
	s_addc_u32 s21, s21, 0
	s_branch .Lcp_dec_tile_a
.Lcp_dec_wout_a:
	s_load_dwordx2 s[20:21], s[0:1], 0x110
	s_sub_u32 s25, s25, 1936
	s_mul_i32 s27, s62, 0x400000
	s_mov_b32 s28, 0x1927800
	s_and_b32 s26, s25, 15
	s_lshr_b32 s25, s25, 4
	s_mov_b32 s18, 1024
	s_mov_b32 s19, 32
	s_mov_b32 s12, 0
	s_mov_b32 s23, 0
	s_waitcnt lgkmcnt(0)
	s_add_u32 s20, s20, s27
	s_addc_u32 s21, s21, 0
	s_branch .Lcp_dec_tile_a
.Lcp_dec_w1_a:
	s_load_dwordx2 s[20:21], s[0:1], 0x118
	s_sub_u32 s25, s25, 2192
	s_mul_i32 s27, s62, 0x1000000
	s_mov_b32 s28, 0x1b27800
	s_and_b32 s26, s25, 63
	s_lshr_b32 s25, s25, 6
	s_mov_b32 s18, 4096
	s_mov_b32 s19, 32
	s_mov_b32 s12, 0
	s_mov_b32 s23, 0
	s_waitcnt lgkmcnt(0)
	s_add_u32 s20, s20, s27
	s_addc_u32 s21, s21, 0
	s_branch .Lcp_dec_tile_a
.Lcp_dec_w2_a:
	s_load_dwordx2 s[20:21], s[0:1], 0x120
	s_sub_u32 s25, s25, 3216
	s_mul_i32 s27, s62, 0x1000000
	s_mov_b32 s28, 0x2327800
	s_and_b32 s26, s25, 15
	s_lshr_b32 s25, s25, 4
	s_mov_b32 s18, 1024
	s_mov_b32 s19, 128
	s_mov_b32 s12, 0
	s_mov_b32 s23, 0
	s_waitcnt lgkmcnt(0)
	s_add_u32 s20, s20, s27
	s_addc_u32 s21, s21, 0
	s_branch .Lcp_dec_tile_a
.Lcp_dec_zero_a:
	s_mov_b32 s12, 3
	s_branch .Lcp_dec_done_a
.Lcp_dec_tile_a:
	s_lshl_b32 s25, s25, 6
	s_lshl_b32 s26, s26, 6
	s_mul_i32 s27, s25, s18
	s_lshl_b32 s27, s27, 2
	s_add_u32 s20, s20, s27
	s_addc_u32 s21, s21, 0
	v_add_u32_e32 v27, s26, v4
	s_sub_u32 s27, s18, 4
	v_min_u32_e32 v27, s27, v27
	v_mul_lo_u32 v28, v3, s18
	v_add_lshl_u32 v28, v28, v27, 2
	s_lshl_b32 s27, s18, 6
	global_load_dwordx4 v[40:43], v28, s[20:21]
	v_add_u32_e32 v28, s27, v28
	global_load_dwordx4 v[44:47], v28, s[20:21]
	v_add_u32_e32 v28, s27, v28
	global_load_dwordx4 v[48:51], v28, s[20:21]
	v_add_u32_e32 v28, s27, v28
	global_load_dwordx4 v[52:55], v28, s[20:21]
	s_mov_b32 s16, 1
	s_lshr_b32 s27, s26, 4
	s_add_u32 s27, s27, s22
	s_lshr_b32 s29, s18, 4
	s_cmp_ge_u32 s27, s29
	s_cbranch_scc0 .Lcp_dec_ok_a
	s_mov_b32 s12, 4
	s_branch .Lcp_dec_done_a
.Lcp_dec_ok_a:
	s_cmp_eq_u32 s12, 1
	s_cbranch_scc1 .Lcp_dec_rm_a
	s_cmp_eq_u32 s23, 0
	s_cbranch_scc1 .Lcp_dec_np_a
	s_cmp_lt_u32 s27, 128
	s_cbranch_scc1 .Lcp_dec_np_a
	s_cmp_eq_u32 s27, 128
	s_cselect_b32 s29, 161, s27
	s_sub_u32 s27, s29, 1
.Lcp_dec_np_a:
	s_mul_i32 s27, s27, s19
	s_lshr_b32 s29, s25, 5
	s_add_u32 s27, s27, s29
	s_lshl_b32 s27, s27, 10
	s_add_u32 s11, s27, s28
	s_branch .Lcp_dec_done_a
.Lcp_dec_rm_a:
	s_lshl_b32 s13, s19, 6
	s_lshl_b32 s27, s27, 4
	s_mul_i32 s27, s27, s13
	s_lshl_b32 s29, s25, 1
	s_add_u32 s27, s27, s29
	s_add_u32 s11, s27, s28
.Lcp_dec_done_a:
.Lcp_noA:
	s_cmp_eq_u32 s9, 3
	s_cbranch_scc1 .Lcp_zero_a
	s_cmp_eq_u32 s16, 1
	s_cbranch_scc1 .Lcp_w4_a
	s_waitcnt vmcnt(0)
	s_branch .Lcp_wd_a
.Lcp_w4_a:
	s_waitcnt vmcnt(4)
.Lcp_wd_a:
	ds_write_b32 v5, v8
	ds_write_b32 v5, v9 offset:4
	ds_write_b32 v5, v10 offset:8
	ds_write_b32 v5, v11 offset:12
	ds_write_b32 v5, v12 offset:4160
	ds_write_b32 v5, v13 offset:4164
	ds_write_b32 v5, v14 offset:4168
	ds_write_b32 v5, v15 offset:4172
	ds_write_b32 v5, v16 offset:8320
	ds_write_b32 v5, v17 offset:8324
	ds_write_b32 v5, v18 offset:8328
	ds_write_b32 v5, v19 offset:8332
	ds_write_b32 v5, v20 offset:12480
	ds_write_b32 v5, v21 offset:12484
	ds_write_b32 v5, v22 offset:12488
	ds_write_b32 v5, v23 offset:12492
	s_waitcnt lgkmcnt(0)
	s_barrier
	s_cmp_eq_u32 s9, 4
	s_cbranch_scc1 .Lcp_pdone_a
	ds_read_b32 v56, v6 offset:0
	ds_read_b32 v57, v6 offset:260
	ds_read_b32 v58, v6 offset:520
	ds_read_b32 v59, v6 offset:780
	ds_read_b32 v60, v6 offset:1040
	ds_read_b32 v61, v6 offset:1300
	ds_read_b32 v62, v6 offset:1560
	ds_read_b32 v63, v6 offset:1820
	ds_read_b32 v64, v6 offset:8320
	ds_read_b32 v65, v6 offset:8580
	ds_read_b32 v66, v6 offset:8840
	ds_read_b32 v67, v6 offset:9100
	ds_read_b32 v68, v6 offset:9360
	ds_read_b32 v69, v6 offset:9620
	ds_read_b32 v70, v6 offset:9880
	ds_read_b32 v71, v6 offset:10140
	s_cmp_eq_u32 s9, 1
	s_cbranch_scc1 .Lcp_prm_a
	v_add_u32_e32 v27, s8, v26
	s_mov_b32 s29, 1024
	s_branch .Lcp_pst_a
.Lcp_prm_a:
	v_mul_lo_u32 v27, v24, s10
	v_lshl_add_u32 v27, v25, 4, v27
	v_add_u32_e32 v27, s8, v27
	s_mov_b32 s29, 64
.Lcp_pst_a:
	v_add_u32_e32 v28, s29, v27
	s_waitcnt lgkmcnt(0)
	v_cvt_pk_bf16_f32 v72, v56, v57
	v_cvt_pk_bf16_f32 v73, v58, v59
	v_cvt_pk_bf16_f32 v74, v60, v61
	v_cvt_pk_bf16_f32 v75, v62, v63
	global_store_dwordx4 v27, v[72:75], s[6:7]
	v_cvt_pk_bf16_f32 v76, v64, v65
	v_cvt_pk_bf16_f32 v77, v66, v67
	v_cvt_pk_bf16_f32 v78, v68, v69
	v_cvt_pk_bf16_f32 v79, v70, v71
	global_store_dwordx4 v28, v[76:79], s[6:7]
	s_branch .Lcp_pdone_a
.Lcp_zero_a:
	v_mov_b32_e32 v56, 0
	v_mov_b32_e32 v57, 0
	v_mov_b32_e32 v58, 0
	v_mov_b32_e32 v59, 0
	v_lshlrev_b32_e32 v27, 4, v2
	v_add_u32_e32 v27, 0xeef800, v27
	s_mov_b32 s29, 56
.Lcp_zloop_a:
	global_store_dwordx4 v27, v[56:59], s[6:7]
	v_add_u32_e32 v27, 0x1000, v27
	s_sub_u32 s29, s29, 1
	s_cmp_lg_u32 s29, 0
	s_cbranch_scc1 .Lcp_zloop_a
.Lcp_pdone_a:
	s_cmp_eq_u32 s12, 5
	s_cbranch_scc1 .Lcp_exit
	s_mov_b32 s24, s15
	s_add_u32 s15, s24, s42
	s_mov_b32 s9, 5
	s_mov_b32 s16, 0
	s_cmp_gt_u32 s15, 0x1890
	s_cbranch_scc1 .Lcp_noB
	s_sub_u32 s14, s15, 2048
	s_mov_b32 s25, s14
	s_cmp_ge_u32 s25, 4240
	s_cbranch_scc1 .Lcp_dec_zero_b
	s_cmp_lt_u32 s25, 656
	s_cbranch_scc1 .Lcp_dec_win_b
	s_cmp_lt_u32 s25, 1680
	s_cbranch_scc1 .Lcp_dec_wm_b
	s_cmp_lt_u32 s25, 1936
	s_cbranch_scc1 .Lcp_dec_wb_b
	s_cmp_lt_u32 s25, 2192
	s_cbranch_scc1 .Lcp_dec_wout_b
	s_cmp_lt_u32 s25, 3216
	s_cbranch_scc1 .Lcp_dec_w1_b
	s_cmp_lt_u32 s25, 4240
	s_cbranch_scc1 .Lcp_dec_w2_b
	s_branch .Lcp_dec_zero_b

.Lcp_dec_done_b:
.Lcp_noB:
	s_cmp_eq_u32 s12, 3
	s_cbranch_scc1 .Lcp_zero_b
	s_cmp_eq_u32 s16, 1
	s_cbranch_scc1 .Lcp_w4_b
	s_waitcnt vmcnt(0)
	s_branch .Lcp_wd_b

.Lcp_wd_b:
	ds_write_b32 v5, v40 offset:16640
	ds_write_b32 v5, v41 offset:16644
	ds_write_b32 v5, v42 offset:16648
	ds_write_b32 v5, v43 offset:16652
	ds_write_b32 v5, v44 offset:20800
	ds_write_b32 v5, v45 offset:20804
	ds_write_b32 v5, v46 offset:20808
	ds_write_b32 v5, v47 offset:20812
	ds_write_b32 v5, v48 offset:24960
	ds_write_b32 v5, v49 offset:24964
	ds_write_b32 v5, v50 offset:24968
	ds_write_b32 v5, v51 offset:24972
	ds_write_b32 v5, v52 offset:29120
	ds_write_b32 v5, v53 offset:29124
	ds_write_b32 v5, v54 offset:29128
	ds_write_b32 v5, v55 offset:29132
	s_waitcnt lgkmcnt(0)
	s_barrier
	s_cmp_eq_u32 s12, 4
	s_cbranch_scc1 .Lcp_pdone_b
	ds_read_b32 v56, v6 offset:16640
	ds_read_b32 v57, v6 offset:16900
	ds_read_b32 v58, v6 offset:17160
	ds_read_b32 v59, v6 offset:17420
	ds_read_b32 v60, v6 offset:17680
	ds_read_b32 v61, v6 offset:17940
	ds_read_b32 v62, v6 offset:18200
	ds_read_b32 v63, v6 offset:18460
	ds_read_b32 v64, v6 offset:24960
	ds_read_b32 v65, v6 offset:25220
	ds_read_b32 v66, v6 offset:25480
	ds_read_b32 v67, v6 offset:25740
	ds_read_b32 v68, v6 offset:26000
	ds_read_b32 v69, v6 offset:26260
	ds_read_b32 v70, v6 offset:26520
	ds_read_b32 v71, v6 offset:26780
	s_cmp_eq_u32 s12, 1
	s_cbranch_scc1 .Lcp_prm_b
	v_add_u32_e32 v27, s11, v26
	s_mov_b32 s29, 1024
	s_branch .Lcp_pst_b
.Lcp_prm_b:
	v_mul_lo_u32 v27, v24, s13
	v_lshl_add_u32 v27, v25, 4, v27
	v_add_u32_e32 v27, s11, v27
	s_mov_b32 s29, 64

.Lcp_pdone_b:
	s_cmp_eq_u32 s9, 5
	s_cbranch_scc1 .Lcp_exit
	s_mov_b32 s24, s15
	s_branch .Lcp_loop
.Lcp_exit:
	s_waitcnt vmcnt(0)
	s_barrier
	s_branch .LBB0_942
	s_add_i32 s25, s24, 0xfffff800
	s_cmpk_gt_u32 s25, 0x28f
	s_cbranch_scc0 .LBB0_861
	s_cmpk_gt_u32 s25, 0x68f
	s_cbranch_scc0 .LBB0_862
	s_cmpk_gt_u32 s25, 0x78f
	s_cbranch_scc0 .LBB0_863
	s_cmpk_gt_u32 s25, 0x88f
	s_cbranch_scc0 .LBB0_864
	s_cmpk_gt_u32 s25, 0xc8f
	s_cbranch_scc0 .LBB0_865
	s_cmpk_gt_u32 s25, 0x108f
	s_mov_b64 s[20:21], -1
	s_cbranch_scc1 .LBB0_866
	s_mov_b64 s[18:19], 0
	s_andn2_b64 vcc, exec, s[20:21]
	s_mov_b64 s[20:21], 0
	s_cbranch_vccz .LBB0_870
